# attention tile loop: the six row-max ops that followed the mid-iteration barrier now run ahead of it, under the LDS/DMA wait (no VALU in the head of the post-barrier segment)
# speedup vs baseline: 1.0078x; 1.0078x over previous
.LBB0_428:
.LBB0_429:
	s_add_i32 s8, s76, 0
	v_add_u32_e32 v90, s8, v207
	v_add_u32_e32 v94, s8, v208
	v_add_u32_e32 v194, s8, v209
	s_waitcnt lgkmcnt(1)
	v_mfma_f32_32x32x16_bf16 v[128:143], v[82:85], v[160:163], v[64:79]
	ds_read_b128 v[82:85], v90
	ds_read_b128 v[90:93], v90 offset:4096
	v_exp_f32_e32 v95, v112
	v_exp_f32_e32 v245, v113
	v_exp_f32_e32 v145, v217
	v_exp_f32_e32 v244, v115
	v_exp_f32_e32 v115, v221
	v_cvt_pk_bf16_f32 v112, v95, v245
	s_waitcnt lgkmcnt(2)
	v_mfma_f32_32x32x16_bf16 v[96:111], v[86:89], v[160:163], v[64:79]
	ds_read_b128 v[86:89], v94
	ds_read_b128 v[232:235], v94 offset:4096
	ds_read_b128 v[236:239], v194
	ds_read_b128 v[240:243], v194 offset:4096
	v_exp_f32_e32 v94, v114
	v_exp_f32_e32 v114, v117
	v_exp_f32_e32 v156, v228
	s_add_i32 s8, s77, s76
	v_cvt_pk_bf16_f32 v113, v94, v244
	s_cmpk_eq_i32 s8, 0x2000
	s_waitcnt lgkmcnt(5)
	v_mfma_f32_32x32x16_bf16 v[128:143], v[82:85], v[164:167], v[128:143]
	v_exp_f32_e32 v85, v216
	v_exp_f32_e32 v84, v218
	v_exp_f32_e32 v144, v219
	s_cselect_b32 s9, s71, 0x2000
	v_cvt_pk_bf16_f32 v82, v85, v145
	s_cmpk_lg_i32 s8, 0x6000
	s_cselect_b32 s76, s9, 0
	s_waitcnt lgkmcnt(4)
	v_mfma_f32_32x32x16_bf16 v[96:111], v[90:93], v[164:167], v[96:111]
	v_add_f32_e32 v90, v94, v244
	v_add_f32_e32 v91, v95, v245
	v_add_f32_e32 v92, v84, v144
	v_add_f32_e32 v93, v85, v145
	v_exp_f32_e32 v94, v120
	v_add_f32_e32 v90, v90, v92
	v_add_f32_e32 v91, v91, v93
	v_exp_f32_e32 v92, v116
	v_exp_f32_e32 v93, v220
	s_waitcnt lgkmcnt(3)
	v_mfma_f32_32x32x16_bf16 v[128:143], v[86:89], v[168:171], v[128:143]
	v_add_f32_e32 v87, v90, v91
	v_cvt_pk_bf16_f32 v83, v84, v144
	v_add_f32_e32 v84, v92, v114
	v_add_f32_e32 v85, v93, v115
	v_exp_f32_e32 v86, v119
	v_add_f32_e32 v89, v84, v85
	v_exp_f32_e32 v85, v118
	v_exp_f32_e32 v88, v222
	v_exp_f32_e32 v90, v223
	s_waitcnt lgkmcnt(2)
	v_mfma_f32_32x32x16_bf16 v[96:111], v[232:235], v[168:171], v[96:111]
	v_cvt_pk_bf16_f32 v114, v92, v114
	v_cvt_pk_bf16_f32 v84, v93, v115
	v_add_f32_e32 v95, v85, v86
	v_add_f32_e32 v233, v88, v90
	v_cvt_pk_bf16_f32 v115, v85, v86
	v_cvt_pk_bf16_f32 v85, v88, v90
	ds_read_b64_tr_b16 v[90:91], v213 offset:24576
	ds_read_b64_tr_b16 v[92:93], v213 offset:26624
	v_exp_f32_e32 v232, v121
	v_exp_f32_e32 v88, v224
	v_exp_f32_e32 v86, v225
	ds_read_b64_tr_b16 v[116:117], v214 offset:24576
	ds_read_b64_tr_b16 v[118:119], v214 offset:26624
	ds_read_b64_tr_b16 v[144:145], v213 offset:28672
	ds_read_b64_tr_b16 v[146:147], v213 offset:30720
	v_add_f32_e32 v120, v94, v232
	v_add_f32_e32 v121, v95, v233
	s_waitcnt lgkmcnt(4)
	v_mfma_f32_32x32x16_bf16 v[48:63], v[90:93], v[112:115], v[48:63]
	v_add_f32_e32 v90, v88, v86
	v_add_f32_e32 v91, v89, v87
	v_exp_f32_e32 v234, v122
	v_add_f32_e32 v152, v120, v90
	v_add_f32_e32 v153, v121, v91
	ds_read_b64_tr_b16 v[90:91], v215 offset:24576
	ds_read_b64_tr_b16 v[92:93], v215 offset:26624
	ds_read_b64_tr_b16 v[148:149], v214 offset:28672
	ds_read_b64_tr_b16 v[150:151], v214 offset:30720
	v_exp_f32_e32 v235, v226
	v_exp_f32_e32 v87, v124
	v_exp_f32_e32 v89, v125
	v_mfma_f32_32x32x16_bf16 v[128:143], v[236:239], v[172:175], v[128:143]
	v_exp_f32_e32 v236, v123
	v_exp_f32_e32 v237, v227
	v_add_f32_e32 v239, v152, v153
	v_exp_f32_e32 v238, v231
	s_min_u32 s8, s4, 32
	s_min_u32 s10, s4, 33
	s_lshl_b32 s8, s8, 17
	s_waitcnt lgkmcnt(6)
	v_mfma_f32_32x32x16_bf16 v[32:47], v[116:119], v[112:115], v[32:47]
	ds_read_b64_tr_b16 v[116:117], v248 offset:24576
	ds_read_b64_tr_b16 v[118:119], v248 offset:26624
	ds_read_b64_tr_b16 v[120:121], v215 offset:28672
	ds_read_b64_tr_b16 v[122:123], v215 offset:30720
	ds_read_b64_tr_b16 v[152:153], v248 offset:28672
	ds_read_b64_tr_b16 v[154:155], v248 offset:30720
	s_add_u32 s8, s36, s8
	s_addc_u32 s9, s37, 0
	s_waitcnt lgkmcnt(8)
	v_mfma_f32_32x32x16_bf16 v[16:31], v[90:93], v[112:115], v[16:31]
	v_add_f32_e32 v92, v234, v236
	v_add_f32_e32 v93, v235, v237
	v_cvt_pk_bf16_f32 v90, v94, v232
	v_add_f32_e32 v95, v92, v93
	v_cvt_pk_bf16_f32 v91, v234, v236
	v_cvt_pk_bf16_f32 v92, v87, v89
	v_exp_f32_e32 v94, v230
	s_waitcnt lgkmcnt(4)
	v_mfma_f32_32x32x16_bf16 v[0:15], v[116:119], v[112:115], v[0:15]
	v_exp_f32_e32 v112, v126
	v_exp_f32_e32 v114, v127
	v_add_f32_e32 v113, v87, v89
	v_cvt_pk_bf16_f32 v93, v112, v114
	s_nop 1
	v_mfma_f32_32x32x16_bf16 v[48:63], v[144:147], v[90:93], v[48:63]
	v_exp_f32_e32 v144, v229
	v_cvt_pk_bf16_f32 v147, v94, v238
	v_cvt_pk_bf16_f32 v145, v235, v237
	v_add_f32_e32 v115, v156, v144
	v_add_f32_e32 v112, v112, v114
	v_add_f32_e32 v113, v113, v115
	v_add_f32_e32 v114, v94, v238
	v_add_f32_e32 v115, v95, v239
	v_mfma_f32_32x32x16_bf16 v[32:47], v[148:151], v[90:93], v[32:47]
	v_add_f32_e32 v112, v112, v114
	v_add_f32_e32 v113, v113, v115
	v_cvt_pk_bf16_f32 v146, v156, v144
	v_add_f32_e32 v87, v112, v113
	ds_read_b64_tr_b16 v[112:113], v213 offset:32768
	ds_read_b64_tr_b16 v[114:115], v213 offset:34816
	v_add_f32_e32 v194, v196, v87
	v_max_f32_e32 v87, v128, v129
	s_waitcnt lgkmcnt(4)
	v_mfma_f32_32x32x16_bf16 v[16:31], v[120:123], v[90:93], v[16:31]
	v_max3_f32 v87, v87, v130, v131
	v_max3_f32 v87, v87, v132, v133
	v_max3_f32 v87, v87, v134, v135
	v_max3_f32 v87, v87, v136, v137
	v_max3_f32 v87, v87, v138, v139
	v_max3_f32 v87, v87, v140, v141
	v_max3_f32 v87, v87, v142, v143
	s_waitcnt lgkmcnt(2)
	v_mfma_f32_32x32x16_bf16 v[0:15], v[152:155], v[90:93], v[0:15]
	ds_read_b64_tr_b16 v[90:91], v214 offset:32768
	ds_read_b64_tr_b16 v[92:93], v214 offset:34816
	ds_read_b64_tr_b16 v[116:117], v213 offset:36864
	ds_read_b64_tr_b16 v[118:119], v213 offset:38912
	v_cvt_pk_bf16_f32 v144, v88, v86
	s_waitcnt lgkmcnt(4)
	v_mfma_f32_32x32x16_bf16 v[48:63], v[112:115], v[82:85], v[48:63]
	ds_read_b64_tr_b16 v[112:113], v215 offset:32768
	ds_read_b64_tr_b16 v[114:115], v215 offset:34816
	ds_read_b64_tr_b16 v[120:121], v214 offset:36864
	ds_read_b64_tr_b16 v[122:123], v214 offset:38912
	s_waitcnt lgkmcnt(6)
	v_mfma_f32_32x32x16_bf16 v[32:47], v[90:93], v[82:85], v[32:47]
	ds_read_b64_tr_b16 v[90:91], v248 offset:32768
	ds_read_b64_tr_b16 v[92:93], v248 offset:34816
	ds_read_b64_tr_b16 v[124:125], v215 offset:36864
	ds_read_b64_tr_b16 v[126:127], v215 offset:38912
	v_mfma_f32_32x32x16_bf16 v[96:111], v[240:243], v[172:175], v[96:111]
	s_waitcnt lgkmcnt(6)
	v_mfma_f32_32x32x16_bf16 v[16:31], v[112:115], v[82:85], v[16:31]
	ds_read_b64_tr_b16 v[112:113], v248 offset:36864
	ds_read_b64_tr_b16 v[114:115], v248 offset:38912
	s_nop 7
	v_max3_f32 v87, v87, v96, v97
	v_max3_f32 v87, v87, v98, v99
	v_max3_f32 v87, v87, v100, v101
	v_max3_f32 v87, v87, v102, v103
	v_max3_f32 v87, v87, v104, v105
	v_max3_f32 v87, v87, v106, v107
	v_max3_f32 v87, v87, v108, v109
	v_max3_f32 v87, v87, v110, v111
	s_waitcnt vmcnt(0)
	s_waitcnt lgkmcnt(0)
	s_barrier
	v_mfma_f32_32x32x16_bf16 v[0:15], v[90:93], v[82:85], v[0:15]
	s_add_u32 s96, s8, s24
	s_addc_u32 s97, s9, s25
	s_add_i32 m0, s43, s76
	s_nop 0
	global_load_lds_dwordx4 v252, s[96:97]
	s_lshl_b32 s8, s10, 17
	s_add_u32 s8, s26, s8
	v_mfma_f32_32x32x16_bf16 v[48:63], v[116:119], v[144:147], v[48:63]
	s_addc_u32 s9, s27, 0
	s_add_u32 s8, s8, 0x40000
	s_addc_u32 s9, s9, 0
	v_mfma_f32_32x32x16_bf16 v[32:47], v[120:123], v[144:147], v[32:47]
	s_mov_b32 m0, s65
	s_nop 0
	global_load_lds_dwordx4 v253, s[8:9]
	s_mov_b32 m0, s66
	s_nop 0
	global_load_lds_dwordx4 v254, s[8:9]
	v_add_f32_e32 v87, v195, v87
	v_cmp_gt_f32_e32 vcc, v87, v81
	v_mfma_f32_32x32x16_bf16 v[16:31], v[124:127], v[144:147], v[16:31]
	v_mfma_f32_32x32x16_bf16 v[0:15], v[112:115], v[144:147], v[0:15]
	s_cbranch_vccz .LBB0_423
	ds_bpermute_b32 v82, v204, v87
	v_max_f32_e32 v83, v87, v87
	s_waitcnt lgkmcnt(0)
	v_max_f32_e32 v82, v82, v82
	v_max_f32_e32 v112, v83, v82
	v_cmp_gt_f32_e32 vcc, v112, v81
	s_and_saveexec_b64 s[8:9], vcc
	s_cbranch_execz .LBB0_422
	v_sub_f32_e32 v65, v112, v195
	v_exp_f32_e64 v64, -v65
	v_xor_b32_e32 v80, 0x80000000, v112
	v_mov_b32_e32 v81, v80
	v_sub_f32_e32 v128, v128, v65
	v_mul_f32_e32 v194, v194, v64
	v_pk_mul_f32 v[62:63], v[62:63], v[64:65] op_sel_hi:[1,0]
	v_pk_mul_f32 v[60:61], v[60:61], v[64:65] op_sel_hi:[1,0]
	v_pk_mul_f32 v[58:59], v[58:59], v[64:65] op_sel_hi:[1,0]
	v_pk_mul_f32 v[56:57], v[56:57], v[64:65] op_sel_hi:[1,0]
	v_pk_mul_f32 v[54:55], v[54:55], v[64:65] op_sel_hi:[1,0]
	v_pk_mul_f32 v[52:53], v[52:53], v[64:65] op_sel_hi:[1,0]
	v_pk_mul_f32 v[50:51], v[50:51], v[64:65] op_sel_hi:[1,0]
	v_pk_mul_f32 v[48:49], v[48:49], v[64:65] op_sel_hi:[1,0]
	v_pk_mul_f32 v[46:47], v[46:47], v[64:65] op_sel_hi:[1,0]
	v_pk_mul_f32 v[44:45], v[44:45], v[64:65] op_sel_hi:[1,0]
	v_pk_mul_f32 v[42:43], v[42:43], v[64:65] op_sel_hi:[1,0]
	v_pk_mul_f32 v[40:41], v[40:41], v[64:65] op_sel_hi:[1,0]
	v_pk_mul_f32 v[38:39], v[38:39], v[64:65] op_sel_hi:[1,0]
	v_pk_mul_f32 v[36:37], v[36:37], v[64:65] op_sel_hi:[1,0]
	v_pk_mul_f32 v[34:35], v[34:35], v[64:65] op_sel_hi:[1,0]
	v_pk_mul_f32 v[32:33], v[32:33], v[64:65] op_sel_hi:[1,0]
	v_pk_mul_f32 v[30:31], v[30:31], v[64:65] op_sel_hi:[1,0]
	v_pk_mul_f32 v[28:29], v[28:29], v[64:65] op_sel_hi:[1,0]
	v_pk_mul_f32 v[26:27], v[26:27], v[64:65] op_sel_hi:[1,0]
	v_pk_mul_f32 v[24:25], v[24:25], v[64:65] op_sel_hi:[1,0]
	v_pk_mul_f32 v[22:23], v[22:23], v[64:65] op_sel_hi:[1,0]
	v_pk_mul_f32 v[20:21], v[20:21], v[64:65] op_sel_hi:[1,0]
	v_pk_mul_f32 v[18:19], v[18:19], v[64:65] op_sel_hi:[1,0]
	v_pk_mul_f32 v[16:17], v[16:17], v[64:65] op_sel_hi:[1,0]
	v_pk_mul_f32 v[14:15], v[14:15], v[64:65] op_sel_hi:[1,0]
	v_pk_mul_f32 v[12:13], v[12:13], v[64:65] op_sel_hi:[1,0]
	v_pk_mul_f32 v[10:11], v[10:11], v[64:65] op_sel_hi:[1,0]
	v_pk_mul_f32 v[8:9], v[8:9], v[64:65] op_sel_hi:[1,0]
	v_pk_mul_f32 v[6:7], v[6:7], v[64:65] op_sel_hi:[1,0]
	v_pk_mul_f32 v[4:5], v[4:5], v[64:65] op_sel_hi:[1,0]
	v_pk_mul_f32 v[2:3], v[2:3], v[64:65] op_sel_hi:[1,0]
	v_pk_mul_f32 v[0:1], v[0:1], v[64:65] op_sel_hi:[1,0]
	v_sub_f32_e32 v129, v129, v65
	v_sub_f32_e32 v130, v130, v65
	v_sub_f32_e32 v131, v131, v65
	v_sub_f32_e32 v132, v132, v65
	v_sub_f32_e32 v133, v133, v65
	v_sub_f32_e32 v134, v134, v65
	v_sub_f32_e32 v135, v135, v65
	v_sub_f32_e32 v136, v136, v65
	v_sub_f32_e32 v137, v137, v65
	v_sub_f32_e32 v138, v138, v65
	v_sub_f32_e32 v139, v139, v65
	v_sub_f32_e32 v140, v140, v65
	v_sub_f32_e32 v141, v141, v65
	v_sub_f32_e32 v142, v142, v65
	v_sub_f32_e32 v143, v143, v65
	v_sub_f32_e32 v96, v96, v65
	v_sub_f32_e32 v97, v97, v65
	v_sub_f32_e32 v98, v98, v65
	v_sub_f32_e32 v99, v99, v65
	v_sub_f32_e32 v100, v100, v65
	v_sub_f32_e32 v101, v101, v65
	v_sub_f32_e32 v102, v102, v65
	v_sub_f32_e32 v103, v103, v65
	v_sub_f32_e32 v104, v104, v65
	v_sub_f32_e32 v105, v105, v65
	v_sub_f32_e32 v106, v106, v65
	v_sub_f32_e32 v107, v107, v65
	v_sub_f32_e32 v108, v108, v65
	v_sub_f32_e32 v109, v109, v65
	v_sub_f32_e32 v110, v110, v65
	v_sub_f32_e32 v111, v111, v65
	v_mov_b32_e32 v82, v80
	v_mov_b32_e32 v83, v80
	v_mov_b32_e32 v84, v80
	v_mov_b32_e32 v85, v80
	v_mov_b32_e32 v86, v80
	v_mov_b32_e32 v87, v80
	v_mov_b32_e32 v88, v80
	v_mov_b32_e32 v89, v80
	v_mov_b32_e32 v90, v80
	v_mov_b32_e32 v91, v80
	v_mov_b32_e32 v92, v80
	v_mov_b32_e32 v93, v80
	v_mov_b32_e32 v94, v80
	v_mov_b32_e32 v95, v80
	v_mov_b64_e32 v[64:65], v[80:81]
	v_mov_b32_e32 v195, v112
	v_mov_b64_e32 v[66:67], v[82:83]
	v_mov_b64_e32 v[68:69], v[84:85]
	v_mov_b64_e32 v[70:71], v[86:87]
	v_mov_b64_e32 v[72:73], v[88:89]
	v_mov_b64_e32 v[74:75], v[90:91]
	v_mov_b64_e32 v[76:77], v[92:93]
	v_mov_b64_e32 v[78:79], v[94:95]
	s_branch .LBB0_422
